# scan: y reduction as a per-chunk 16x16 reduce-scatter (DPP bank-masked butterfly) instead of 16 per-step reductions; packed dot products; one LDS wait per step
# speedup vs baseline: 1.1496x; 1.0112x over previous
; DI void phase_scan(const Params& P, int l, char* smem) {
;     ...
;       {
;         float4 Ar[4], Aw[4], Ak[4], Aa[4], Ab[4], Br[4], Bw[4], Bk[4], Ba[4], Bb[4];
;         float Av[4], Bv[4];
;         SCAN_LOAD(A, 0);
;         SCAN_LOAD(B, 1);
;         SCAN_STEPS(A, 0);
;         SCAN_LOAD(A, 2);
;         SCAN_STEPS(B, 1);
;         SCAN_LOAD(B, 3);
;         SCAN_STEPS(A, 2);
;         SCAN_STEPS(B, 3);
;       }
.LBB0_513:
	s_add_i32 s8, s20, 1
	s_bitcmp1_b32 s20, 0
	s_cselect_b32 s9, 0x6000, 0
	v_lshl_or_b32 v219, v172, 2, s9
	s_lshl_b32 s10, s19, 2
	s_or_b32 s9, s9, s10
	v_lshl_add_u32 v218, v170, 2, s9
	ds_read_b128 v[40:43], v219 offset:512
	ds_read_b32 v60, v218 offset:1280
	ds_read_b128 v[44:47], v219 offset:768
	ds_read_b128 v[48:51], v219 offset:256
	ds_read_b128 v[52:55], v219 offset:1024
	ds_read_b128 v[56:59], v219
	ds_read_b128 v[64:67], v219 offset:2048
	ds_read_b32 v84, v218 offset:2816
	ds_read_b128 v[68:71], v219 offset:2304
	ds_read_b128 v[72:75], v219 offset:1792
	ds_read_b128 v[76:79], v219 offset:2560
	ds_read_b128 v[80:83], v219 offset:1536
	s_cmp_lt_u32 s20, 16
	s_movk_i32 s9, 0x41ff
	s_cselect_b32 s9, 0xff, s9
	s_andn2_b64 vcc, exec, s[16:17]
	s_mov_b32 s10, 0x10001
	s_mov_b32 s11, 0x10001
	s_waitcnt lgkmcnt(10)
	v_pk_mul_f32 v[156:157], v[60:61], v[40:41] op_sel_hi:[0,1]
	v_pk_mul_f32 v[158:159], v[60:61], v[42:43] op_sel_hi:[0,1]
	s_waitcnt lgkmcnt(4)
	ds_read_b128 v[88:91], v219 offset:3584
	ds_read_b32 v108, v218 offset:4352
	ds_read_b128 v[92:95], v219 offset:3840
	ds_read_b128 v[96:99], v219 offset:3328
	ds_read_b128 v[100:103], v219 offset:4096
	ds_read_b128 v[104:107], v219 offset:3072
	v_pk_mul_f32 v[164:165], v[126:127], v[44:45]
	v_pk_fma_f32 v[164:165], v[128:129], v[46:47], v[164:165]
	v_add_f32_e32 v164, v164, v165
	v_pk_fma_f32 v[156:157], v[126:127], v[48:49], v[156:157]
	v_pk_fma_f32 v[158:159], v[128:129], v[50:51], v[158:159]
	v_add_f32_dpp v164, v164, v164 quad_perm:[1,0,3,2] row_mask:0xf bank_mask:0xf bound_ctrl:1
	s_nop 0
	s_nop 0
	v_add_f32_dpp v164, v164, v164 quad_perm:[2,3,0,1] row_mask:0xf bank_mask:0xf bound_ctrl:1
	s_nop 0
	v_pk_mul_f32 v[160:161], v[84:85], v[64:65] op_sel_hi:[0,1]
	v_add_f32_dpp v164, v164, v164 row_half_mirror row_mask:0xf bank_mask:0xf bound_ctrl:1
	v_pk_mul_f32 v[162:163], v[84:85], v[66:67] op_sel_hi:[0,1]
	s_nop 0
	v_add_f32_dpp v164, v164, v164 row_mirror row_mask:0xf bank_mask:0xf bound_ctrl:1
	v_pk_fma_f32 v[126:127], v[164:165], v[52:53], v[156:157] op_sel_hi:[0,1,1]
	v_pk_fma_f32 v[128:129], v[164:165], v[54:55], v[158:159] op_sel_hi:[0,1,1]
	s_waitcnt lgkmcnt(4)
	ds_read_b128 v[132:135], v219 offset:5120
	ds_read_b32 v152, v218 offset:5888
	ds_read_b128 v[136:139], v219 offset:5376
	ds_read_b128 v[140:143], v219 offset:4864
	ds_read_b128 v[144:147], v219 offset:5632
	ds_read_b128 v[148:151], v219 offset:4608
	v_pk_mul_f32 v[164:165], v[126:127], v[68:69]
	v_pk_fma_f32 v[164:165], v[128:129], v[70:71], v[164:165]
	v_add_f32_e32 v164, v164, v165
	v_pk_fma_f32 v[160:161], v[126:127], v[72:73], v[160:161]
	v_pk_fma_f32 v[162:163], v[128:129], v[74:75], v[162:163]
	v_add_f32_dpp v164, v164, v164 quad_perm:[1,0,3,2] row_mask:0xf bank_mask:0xf bound_ctrl:1
	v_pk_mul_f32 v[166:167], v[126:127], v[56:57]
	v_pk_fma_f32 v[166:167], v[128:129], v[58:59], v[166:167]
	v_add_f32_dpp v164, v164, v164 quad_perm:[2,3,0,1] row_mask:0xf bank_mask:0xf bound_ctrl:1
	v_add_f32_e32 v12, v166, v167
	v_pk_mul_f32 v[156:157], v[108:109], v[88:89] op_sel_hi:[0,1]
	v_add_f32_dpp v164, v164, v164 row_half_mirror row_mask:0xf bank_mask:0xf bound_ctrl:1
	v_pk_mul_f32 v[158:159], v[108:109], v[90:91] op_sel_hi:[0,1]
	s_nop 0
	v_add_f32_dpp v164, v164, v164 row_mirror row_mask:0xf bank_mask:0xf bound_ctrl:1
	v_pk_fma_f32 v[126:127], v[164:165], v[76:77], v[160:161] op_sel_hi:[0,1,1]
	v_pk_fma_f32 v[128:129], v[164:165], v[78:79], v[162:163] op_sel_hi:[0,1,1]
	s_waitcnt lgkmcnt(4)
	ds_read_b128 v[40:43], v219 offset:6656
	ds_read_b32 v60, v218 offset:7424
	ds_read_b128 v[44:47], v219 offset:6912
	ds_read_b128 v[48:51], v219 offset:6400
	ds_read_b128 v[52:55], v219 offset:7168
	ds_read_b128 v[56:59], v219 offset:6144
	v_pk_mul_f32 v[164:165], v[126:127], v[92:93]
	v_pk_fma_f32 v[164:165], v[128:129], v[94:95], v[164:165]
	v_add_f32_e32 v164, v164, v165
	v_pk_fma_f32 v[156:157], v[126:127], v[96:97], v[156:157]
	v_pk_fma_f32 v[158:159], v[128:129], v[98:99], v[158:159]
	v_add_f32_dpp v164, v164, v164 quad_perm:[1,0,3,2] row_mask:0xf bank_mask:0xf bound_ctrl:1
	v_pk_mul_f32 v[166:167], v[126:127], v[80:81]
	v_pk_fma_f32 v[166:167], v[128:129], v[82:83], v[166:167]
	v_add_f32_dpp v164, v164, v164 quad_perm:[2,3,0,1] row_mask:0xf bank_mask:0xf bound_ctrl:1
	v_add_f32_e32 v13, v166, v167
	v_pk_mul_f32 v[160:161], v[152:153], v[132:133] op_sel_hi:[0,1]
	v_add_f32_dpp v164, v164, v164 row_half_mirror row_mask:0xf bank_mask:0xf bound_ctrl:1
	v_pk_mul_f32 v[162:163], v[152:153], v[134:135] op_sel_hi:[0,1]
	s_nop 0
	v_add_f32_dpp v164, v164, v164 row_mirror row_mask:0xf bank_mask:0xf bound_ctrl:1
	v_pk_fma_f32 v[126:127], v[164:165], v[100:101], v[156:157] op_sel_hi:[0,1,1]
	v_pk_fma_f32 v[128:129], v[164:165], v[102:103], v[158:159] op_sel_hi:[0,1,1]
	s_waitcnt lgkmcnt(4)
	ds_read_b128 v[64:67], v219 offset:8192
	ds_read_b32 v84, v218 offset:8960
	ds_read_b128 v[68:71], v219 offset:8448
	ds_read_b128 v[72:75], v219 offset:7936
	ds_read_b128 v[76:79], v219 offset:8704
	ds_read_b128 v[80:83], v219 offset:7680
	v_pk_mul_f32 v[164:165], v[126:127], v[136:137]
	v_pk_fma_f32 v[164:165], v[128:129], v[138:139], v[164:165]
	v_add_f32_e32 v164, v164, v165
	v_pk_fma_f32 v[160:161], v[126:127], v[140:141], v[160:161]
	v_pk_fma_f32 v[162:163], v[128:129], v[142:143], v[162:163]
	v_add_f32_dpp v164, v164, v164 quad_perm:[1,0,3,2] row_mask:0xf bank_mask:0xf bound_ctrl:1
	v_pk_mul_f32 v[166:167], v[126:127], v[104:105]
	v_pk_fma_f32 v[166:167], v[128:129], v[106:107], v[166:167]
	v_add_f32_dpp v164, v164, v164 quad_perm:[2,3,0,1] row_mask:0xf bank_mask:0xf bound_ctrl:1
	v_add_f32_e32 v14, v166, v167
	v_pk_mul_f32 v[156:157], v[60:61], v[40:41] op_sel_hi:[0,1]
	v_add_f32_dpp v164, v164, v164 row_half_mirror row_mask:0xf bank_mask:0xf bound_ctrl:1
	v_pk_mul_f32 v[158:159], v[60:61], v[42:43] op_sel_hi:[0,1]
	s_nop 0
	v_add_f32_dpp v164, v164, v164 row_mirror row_mask:0xf bank_mask:0xf bound_ctrl:1
	v_pk_fma_f32 v[126:127], v[164:165], v[144:145], v[160:161] op_sel_hi:[0,1,1]
	v_pk_fma_f32 v[128:129], v[164:165], v[146:147], v[162:163] op_sel_hi:[0,1,1]
	s_waitcnt lgkmcnt(4)
; DI void phase_scan(const Params& P, int l, char* smem) {
;     ...
;       {
;         float4 Ar[4], Aw[4], Ak[4], Aa[4], Ab[4], Br[4], Bw[4], Bk[4], Ba[4], Bb[4];
;         float Av[4], Bv[4];
;         SCAN_LOAD(A, 0);
;         SCAN_LOAD(B, 1);
;         SCAN_STEPS(A, 0);
;         SCAN_LOAD(A, 2);
;         SCAN_STEPS(B, 1);
;         SCAN_LOAD(B, 3);
;         SCAN_STEPS(A, 2);
;         SCAN_STEPS(B, 3);
;       }
	ds_read_b128 v[88:91], v219 offset:9728
	ds_read_b32 v108, v218 offset:10496
	ds_read_b128 v[92:95], v219 offset:9984
	ds_read_b128 v[96:99], v219 offset:9472
	ds_read_b128 v[100:103], v219 offset:10240
	ds_read_b128 v[104:107], v219 offset:9216
	v_pk_mul_f32 v[164:165], v[126:127], v[44:45]
	v_pk_fma_f32 v[164:165], v[128:129], v[46:47], v[164:165]
	v_add_f32_e32 v164, v164, v165
	v_pk_fma_f32 v[156:157], v[126:127], v[48:49], v[156:157]
	v_pk_fma_f32 v[158:159], v[128:129], v[50:51], v[158:159]
	v_add_f32_dpp v164, v164, v164 quad_perm:[1,0,3,2] row_mask:0xf bank_mask:0xf bound_ctrl:1
	v_pk_mul_f32 v[166:167], v[126:127], v[148:149]
	v_pk_fma_f32 v[166:167], v[128:129], v[150:151], v[166:167]
	v_add_f32_dpp v164, v164, v164 quad_perm:[2,3,0,1] row_mask:0xf bank_mask:0xf bound_ctrl:1
	v_add_f32_e32 v15, v166, v167
	v_pk_mul_f32 v[160:161], v[84:85], v[64:65] op_sel_hi:[0,1]
	v_add_f32_dpp v164, v164, v164 row_half_mirror row_mask:0xf bank_mask:0xf bound_ctrl:1
	v_pk_mul_f32 v[162:163], v[84:85], v[66:67] op_sel_hi:[0,1]
	s_nop 0
	v_add_f32_dpp v164, v164, v164 row_mirror row_mask:0xf bank_mask:0xf bound_ctrl:1
	v_pk_fma_f32 v[126:127], v[164:165], v[52:53], v[156:157] op_sel_hi:[0,1,1]
	v_pk_fma_f32 v[128:129], v[164:165], v[54:55], v[158:159] op_sel_hi:[0,1,1]
	s_waitcnt lgkmcnt(4)
	ds_read_b128 v[132:135], v219 offset:11264
	ds_read_b32 v152, v218 offset:12032
	ds_read_b128 v[136:139], v219 offset:11520
	ds_read_b128 v[140:143], v219 offset:11008
	ds_read_b128 v[144:147], v219 offset:11776
	ds_read_b128 v[148:151], v219 offset:10752
	v_pk_mul_f32 v[164:165], v[126:127], v[68:69]
	v_pk_fma_f32 v[164:165], v[128:129], v[70:71], v[164:165]
	v_add_f32_e32 v164, v164, v165
	v_pk_fma_f32 v[160:161], v[126:127], v[72:73], v[160:161]
	v_pk_fma_f32 v[162:163], v[128:129], v[74:75], v[162:163]
	v_add_f32_dpp v164, v164, v164 quad_perm:[1,0,3,2] row_mask:0xf bank_mask:0xf bound_ctrl:1
	v_pk_mul_f32 v[166:167], v[126:127], v[56:57]
	v_pk_fma_f32 v[166:167], v[128:129], v[58:59], v[166:167]
	v_add_f32_dpp v164, v164, v164 quad_perm:[2,3,0,1] row_mask:0xf bank_mask:0xf bound_ctrl:1
	v_add_f32_e32 v16, v166, v167
	v_pk_mul_f32 v[156:157], v[108:109], v[88:89] op_sel_hi:[0,1]
	v_add_f32_dpp v164, v164, v164 row_half_mirror row_mask:0xf bank_mask:0xf bound_ctrl:1
	v_pk_mul_f32 v[158:159], v[108:109], v[90:91] op_sel_hi:[0,1]
	s_nop 0
	v_add_f32_dpp v164, v164, v164 row_mirror row_mask:0xf bank_mask:0xf bound_ctrl:1
	v_pk_fma_f32 v[126:127], v[164:165], v[76:77], v[160:161] op_sel_hi:[0,1,1]
	v_pk_fma_f32 v[128:129], v[164:165], v[78:79], v[162:163] op_sel_hi:[0,1,1]
	s_waitcnt lgkmcnt(4)
	ds_read_b128 v[40:43], v219 offset:12800
	ds_read_b32 v60, v218 offset:13568
	ds_read_b128 v[44:47], v219 offset:13056
	ds_read_b128 v[48:51], v219 offset:12544
	ds_read_b128 v[52:55], v219 offset:13312
	ds_read_b128 v[56:59], v219 offset:12288
	v_pk_mul_f32 v[164:165], v[126:127], v[92:93]
	v_pk_fma_f32 v[164:165], v[128:129], v[94:95], v[164:165]
	v_add_f32_e32 v164, v164, v165
	v_pk_fma_f32 v[156:157], v[126:127], v[96:97], v[156:157]
	v_pk_fma_f32 v[158:159], v[128:129], v[98:99], v[158:159]
	v_add_f32_dpp v164, v164, v164 quad_perm:[1,0,3,2] row_mask:0xf bank_mask:0xf bound_ctrl:1
	v_pk_mul_f32 v[166:167], v[126:127], v[80:81]
	v_pk_fma_f32 v[166:167], v[128:129], v[82:83], v[166:167]
	v_add_f32_dpp v164, v164, v164 quad_perm:[2,3,0,1] row_mask:0xf bank_mask:0xf bound_ctrl:1
	v_add_f32_e32 v17, v166, v167
	v_pk_mul_f32 v[160:161], v[152:153], v[132:133] op_sel_hi:[0,1]
	v_add_f32_dpp v164, v164, v164 row_half_mirror row_mask:0xf bank_mask:0xf bound_ctrl:1
	v_pk_mul_f32 v[162:163], v[152:153], v[134:135] op_sel_hi:[0,1]
	s_nop 0
	v_add_f32_dpp v164, v164, v164 row_mirror row_mask:0xf bank_mask:0xf bound_ctrl:1
	v_pk_fma_f32 v[126:127], v[164:165], v[100:101], v[156:157] op_sel_hi:[0,1,1]
	v_pk_fma_f32 v[128:129], v[164:165], v[102:103], v[158:159] op_sel_hi:[0,1,1]
	s_waitcnt lgkmcnt(4)
	ds_read_b128 v[64:67], v219 offset:14336
	ds_read_b32 v84, v218 offset:15104
	ds_read_b128 v[68:71], v219 offset:14592
	ds_read_b128 v[72:75], v219 offset:14080
	ds_read_b128 v[76:79], v219 offset:14848
	ds_read_b128 v[80:83], v219 offset:13824
	v_pk_mul_f32 v[164:165], v[126:127], v[136:137]
	v_pk_fma_f32 v[164:165], v[128:129], v[138:139], v[164:165]
	v_add_f32_e32 v164, v164, v165
	v_pk_fma_f32 v[160:161], v[126:127], v[140:141], v[160:161]
	v_pk_fma_f32 v[162:163], v[128:129], v[142:143], v[162:163]
	v_add_f32_dpp v164, v164, v164 quad_perm:[1,0,3,2] row_mask:0xf bank_mask:0xf bound_ctrl:1
	v_pk_mul_f32 v[166:167], v[126:127], v[104:105]
	v_pk_fma_f32 v[166:167], v[128:129], v[106:107], v[166:167]
	v_add_f32_dpp v164, v164, v164 quad_perm:[2,3,0,1] row_mask:0xf bank_mask:0xf bound_ctrl:1
	v_add_f32_e32 v18, v166, v167
	v_pk_mul_f32 v[156:157], v[60:61], v[40:41] op_sel_hi:[0,1]
	v_add_f32_dpp v164, v164, v164 row_half_mirror row_mask:0xf bank_mask:0xf bound_ctrl:1
	v_pk_mul_f32 v[158:159], v[60:61], v[42:43] op_sel_hi:[0,1]
	s_nop 0
	v_add_f32_dpp v164, v164, v164 row_mirror row_mask:0xf bank_mask:0xf bound_ctrl:1
	v_pk_fma_f32 v[126:127], v[164:165], v[144:145], v[160:161] op_sel_hi:[0,1,1]
	v_pk_fma_f32 v[128:129], v[164:165], v[146:147], v[162:163] op_sel_hi:[0,1,1]
	s_waitcnt lgkmcnt(4)
; DI void phase_scan(const Params& P, int l, char* smem) {
;     ...
;       {
;         float4 Ar[4], Aw[4], Ak[4], Aa[4], Ab[4], Br[4], Bw[4], Bk[4], Ba[4], Bb[4];
;         float Av[4], Bv[4];
;         SCAN_LOAD(A, 0);
;         SCAN_LOAD(B, 1);
;         SCAN_STEPS(A, 0);
;         SCAN_LOAD(A, 2);
;         SCAN_STEPS(B, 1);
;         SCAN_LOAD(B, 3);
;         SCAN_STEPS(A, 2);
;         SCAN_STEPS(B, 3);
;       }
	ds_read_b128 v[88:91], v219 offset:15872
	ds_read_b32 v108, v218 offset:16640
	ds_read_b128 v[92:95], v219 offset:16128
	ds_read_b128 v[96:99], v219 offset:15616
	ds_read_b128 v[100:103], v219 offset:16384
	ds_read_b128 v[104:107], v219 offset:15360
	v_pk_mul_f32 v[164:165], v[126:127], v[44:45]
	v_pk_fma_f32 v[164:165], v[128:129], v[46:47], v[164:165]
	v_add_f32_e32 v164, v164, v165
	v_pk_fma_f32 v[156:157], v[126:127], v[48:49], v[156:157]
	v_pk_fma_f32 v[158:159], v[128:129], v[50:51], v[158:159]
	v_add_f32_dpp v164, v164, v164 quad_perm:[1,0,3,2] row_mask:0xf bank_mask:0xf bound_ctrl:1
	v_pk_mul_f32 v[166:167], v[126:127], v[148:149]
	v_pk_fma_f32 v[166:167], v[128:129], v[150:151], v[166:167]
	v_add_f32_dpp v164, v164, v164 quad_perm:[2,3,0,1] row_mask:0xf bank_mask:0xf bound_ctrl:1
	v_add_f32_e32 v19, v166, v167
	v_pk_mul_f32 v[160:161], v[84:85], v[64:65] op_sel_hi:[0,1]
	v_add_f32_dpp v164, v164, v164 row_half_mirror row_mask:0xf bank_mask:0xf bound_ctrl:1
	v_pk_mul_f32 v[162:163], v[84:85], v[66:67] op_sel_hi:[0,1]
	s_nop 0
	v_add_f32_dpp v164, v164, v164 row_mirror row_mask:0xf bank_mask:0xf bound_ctrl:1
	v_pk_fma_f32 v[126:127], v[164:165], v[52:53], v[156:157] op_sel_hi:[0,1,1]
	v_pk_fma_f32 v[128:129], v[164:165], v[54:55], v[158:159] op_sel_hi:[0,1,1]
	s_waitcnt lgkmcnt(4)
	ds_read_b128 v[132:135], v219 offset:17408
	ds_read_b32 v152, v218 offset:18176
	ds_read_b128 v[136:139], v219 offset:17664
	ds_read_b128 v[140:143], v219 offset:17152
	ds_read_b128 v[144:147], v219 offset:17920
	ds_read_b128 v[148:151], v219 offset:16896
	v_pk_mul_f32 v[164:165], v[126:127], v[68:69]
	v_pk_fma_f32 v[164:165], v[128:129], v[70:71], v[164:165]
	v_add_f32_e32 v164, v164, v165
	v_pk_fma_f32 v[160:161], v[126:127], v[72:73], v[160:161]
	v_pk_fma_f32 v[162:163], v[128:129], v[74:75], v[162:163]
	v_add_f32_dpp v164, v164, v164 quad_perm:[1,0,3,2] row_mask:0xf bank_mask:0xf bound_ctrl:1
	v_pk_mul_f32 v[166:167], v[126:127], v[56:57]
	v_pk_fma_f32 v[166:167], v[128:129], v[58:59], v[166:167]
	v_add_f32_dpp v164, v164, v164 quad_perm:[2,3,0,1] row_mask:0xf bank_mask:0xf bound_ctrl:1
	v_add_f32_e32 v20, v166, v167
	v_pk_mul_f32 v[156:157], v[108:109], v[88:89] op_sel_hi:[0,1]
	v_add_f32_dpp v164, v164, v164 row_half_mirror row_mask:0xf bank_mask:0xf bound_ctrl:1
	v_pk_mul_f32 v[158:159], v[108:109], v[90:91] op_sel_hi:[0,1]
	s_nop 0
	v_add_f32_dpp v164, v164, v164 row_mirror row_mask:0xf bank_mask:0xf bound_ctrl:1
	v_pk_fma_f32 v[126:127], v[164:165], v[76:77], v[160:161] op_sel_hi:[0,1,1]
	v_pk_fma_f32 v[128:129], v[164:165], v[78:79], v[162:163] op_sel_hi:[0,1,1]
	s_waitcnt lgkmcnt(4)
	ds_read_b128 v[40:43], v219 offset:18944
	ds_read_b32 v60, v218 offset:19712
	ds_read_b128 v[44:47], v219 offset:19200
	ds_read_b128 v[48:51], v219 offset:18688
	ds_read_b128 v[52:55], v219 offset:19456
	ds_read_b128 v[56:59], v219 offset:18432
	v_pk_mul_f32 v[164:165], v[126:127], v[92:93]
	v_pk_fma_f32 v[164:165], v[128:129], v[94:95], v[164:165]
	v_add_f32_e32 v164, v164, v165
	v_pk_fma_f32 v[156:157], v[126:127], v[96:97], v[156:157]
	v_pk_fma_f32 v[158:159], v[128:129], v[98:99], v[158:159]
	v_add_f32_dpp v164, v164, v164 quad_perm:[1,0,3,2] row_mask:0xf bank_mask:0xf bound_ctrl:1
	v_pk_mul_f32 v[166:167], v[126:127], v[80:81]
	v_pk_fma_f32 v[166:167], v[128:129], v[82:83], v[166:167]
	v_add_f32_dpp v164, v164, v164 quad_perm:[2,3,0,1] row_mask:0xf bank_mask:0xf bound_ctrl:1
	v_add_f32_e32 v21, v166, v167
	v_pk_mul_f32 v[160:161], v[152:153], v[132:133] op_sel_hi:[0,1]
	v_add_f32_dpp v164, v164, v164 row_half_mirror row_mask:0xf bank_mask:0xf bound_ctrl:1
	v_pk_mul_f32 v[162:163], v[152:153], v[134:135] op_sel_hi:[0,1]
	s_nop 0
	v_add_f32_dpp v164, v164, v164 row_mirror row_mask:0xf bank_mask:0xf bound_ctrl:1
	v_pk_fma_f32 v[126:127], v[164:165], v[100:101], v[156:157] op_sel_hi:[0,1,1]
	v_pk_fma_f32 v[128:129], v[164:165], v[102:103], v[158:159] op_sel_hi:[0,1,1]
	s_waitcnt lgkmcnt(4)
	ds_read_b128 v[64:67], v219 offset:20480
	ds_read_b32 v84, v218 offset:21248
	ds_read_b128 v[68:71], v219 offset:20736
	ds_read_b128 v[72:75], v219 offset:20224
	ds_read_b128 v[76:79], v219 offset:20992
	ds_read_b128 v[80:83], v219 offset:19968
	v_pk_mul_f32 v[164:165], v[126:127], v[136:137]
	v_pk_fma_f32 v[164:165], v[128:129], v[138:139], v[164:165]
	v_add_f32_e32 v164, v164, v165
	v_pk_fma_f32 v[160:161], v[126:127], v[140:141], v[160:161]
	v_pk_fma_f32 v[162:163], v[128:129], v[142:143], v[162:163]
	v_add_f32_dpp v164, v164, v164 quad_perm:[1,0,3,2] row_mask:0xf bank_mask:0xf bound_ctrl:1
	v_pk_mul_f32 v[166:167], v[126:127], v[104:105]
	v_pk_fma_f32 v[166:167], v[128:129], v[106:107], v[166:167]
	v_add_f32_dpp v164, v164, v164 quad_perm:[2,3,0,1] row_mask:0xf bank_mask:0xf bound_ctrl:1
	v_add_f32_e32 v22, v166, v167
	v_pk_mul_f32 v[156:157], v[60:61], v[40:41] op_sel_hi:[0,1]
	v_add_f32_dpp v164, v164, v164 row_half_mirror row_mask:0xf bank_mask:0xf bound_ctrl:1
	v_pk_mul_f32 v[158:159], v[60:61], v[42:43] op_sel_hi:[0,1]
	s_nop 0
	v_add_f32_dpp v164, v164, v164 row_mirror row_mask:0xf bank_mask:0xf bound_ctrl:1
	v_pk_fma_f32 v[126:127], v[164:165], v[144:145], v[160:161] op_sel_hi:[0,1,1]
	v_pk_fma_f32 v[128:129], v[164:165], v[146:147], v[162:163] op_sel_hi:[0,1,1]
	s_waitcnt lgkmcnt(4)
; DI void phase_scan(const Params& P, int l, char* smem) {
;     ...
;       {
;         float4 Ar[4], Aw[4], Ak[4], Aa[4], Ab[4], Br[4], Bw[4], Bk[4], Ba[4], Bb[4];
;         float Av[4], Bv[4];
;         SCAN_LOAD(A, 0);
;         SCAN_LOAD(B, 1);
;         SCAN_STEPS(A, 0);
;         SCAN_LOAD(A, 2);
;         SCAN_STEPS(B, 1);
;         SCAN_LOAD(B, 3);
;         SCAN_STEPS(A, 2);
;         SCAN_STEPS(B, 3);
;       }
	ds_read_b128 v[88:91], v219 offset:22016
	ds_read_b32 v108, v218 offset:22784
	ds_read_b128 v[92:95], v219 offset:22272
	ds_read_b128 v[96:99], v219 offset:21760
	ds_read_b128 v[100:103], v219 offset:22528
	ds_read_b128 v[104:107], v219 offset:21504
	v_pk_mul_f32 v[164:165], v[126:127], v[44:45]
	v_pk_fma_f32 v[164:165], v[128:129], v[46:47], v[164:165]
	v_add_f32_e32 v164, v164, v165
	v_pk_fma_f32 v[156:157], v[126:127], v[48:49], v[156:157]
	v_pk_fma_f32 v[158:159], v[128:129], v[50:51], v[158:159]
	v_add_f32_dpp v164, v164, v164 quad_perm:[1,0,3,2] row_mask:0xf bank_mask:0xf bound_ctrl:1
	v_pk_mul_f32 v[166:167], v[126:127], v[148:149]
	v_pk_fma_f32 v[166:167], v[128:129], v[150:151], v[166:167]
	v_add_f32_dpp v164, v164, v164 quad_perm:[2,3,0,1] row_mask:0xf bank_mask:0xf bound_ctrl:1
	v_add_f32_e32 v23, v166, v167
	v_pk_mul_f32 v[160:161], v[84:85], v[64:65] op_sel_hi:[0,1]
	v_add_f32_dpp v164, v164, v164 row_half_mirror row_mask:0xf bank_mask:0xf bound_ctrl:1
	v_pk_mul_f32 v[162:163], v[84:85], v[66:67] op_sel_hi:[0,1]
	s_nop 0
	v_add_f32_dpp v164, v164, v164 row_mirror row_mask:0xf bank_mask:0xf bound_ctrl:1
	v_pk_fma_f32 v[126:127], v[164:165], v[52:53], v[156:157] op_sel_hi:[0,1,1]
	v_pk_fma_f32 v[128:129], v[164:165], v[54:55], v[158:159] op_sel_hi:[0,1,1]
	s_waitcnt lgkmcnt(4)
	ds_read_b128 v[132:135], v219 offset:23552
	ds_read_b32 v152, v218 offset:24320
	ds_read_b128 v[136:139], v219 offset:23808
	ds_read_b128 v[140:143], v219 offset:23296
	ds_read_b128 v[144:147], v219 offset:24064
	ds_read_b128 v[148:151], v219 offset:23040
	v_pk_mul_f32 v[164:165], v[126:127], v[68:69]
	v_pk_fma_f32 v[164:165], v[128:129], v[70:71], v[164:165]
	v_add_f32_e32 v164, v164, v165
	v_pk_fma_f32 v[160:161], v[126:127], v[72:73], v[160:161]
	v_pk_fma_f32 v[162:163], v[128:129], v[74:75], v[162:163]
	v_add_f32_dpp v164, v164, v164 quad_perm:[1,0,3,2] row_mask:0xf bank_mask:0xf bound_ctrl:1
	v_pk_mul_f32 v[166:167], v[126:127], v[56:57]
	v_pk_fma_f32 v[166:167], v[128:129], v[58:59], v[166:167]
	v_add_f32_dpp v164, v164, v164 quad_perm:[2,3,0,1] row_mask:0xf bank_mask:0xf bound_ctrl:1
	v_add_f32_e32 v24, v166, v167
	v_pk_mul_f32 v[156:157], v[108:109], v[88:89] op_sel_hi:[0,1]
	v_add_f32_dpp v164, v164, v164 row_half_mirror row_mask:0xf bank_mask:0xf bound_ctrl:1
	v_pk_mul_f32 v[158:159], v[108:109], v[90:91] op_sel_hi:[0,1]
	s_nop 0
	v_add_f32_dpp v164, v164, v164 row_mirror row_mask:0xf bank_mask:0xf bound_ctrl:1
	v_pk_fma_f32 v[126:127], v[164:165], v[76:77], v[160:161] op_sel_hi:[0,1,1]
	v_pk_fma_f32 v[128:129], v[164:165], v[78:79], v[162:163] op_sel_hi:[0,1,1]
	s_waitcnt lgkmcnt(4)
	v_pk_mul_f32 v[164:165], v[126:127], v[92:93]
	v_pk_fma_f32 v[164:165], v[128:129], v[94:95], v[164:165]
	v_add_f32_e32 v164, v164, v165
	v_pk_fma_f32 v[156:157], v[126:127], v[96:97], v[156:157]
	v_pk_fma_f32 v[158:159], v[128:129], v[98:99], v[158:159]
	v_add_f32_dpp v164, v164, v164 quad_perm:[1,0,3,2] row_mask:0xf bank_mask:0xf bound_ctrl:1
	v_pk_mul_f32 v[166:167], v[126:127], v[80:81]
	v_pk_fma_f32 v[166:167], v[128:129], v[82:83], v[166:167]
	v_add_f32_dpp v164, v164, v164 quad_perm:[2,3,0,1] row_mask:0xf bank_mask:0xf bound_ctrl:1
	v_add_f32_e32 v25, v166, v167
	v_pk_mul_f32 v[160:161], v[152:153], v[132:133] op_sel_hi:[0,1]
	v_add_f32_dpp v164, v164, v164 row_half_mirror row_mask:0xf bank_mask:0xf bound_ctrl:1
	v_pk_mul_f32 v[162:163], v[152:153], v[134:135] op_sel_hi:[0,1]
	s_nop 0
	v_add_f32_dpp v164, v164, v164 row_mirror row_mask:0xf bank_mask:0xf bound_ctrl:1
	v_pk_fma_f32 v[126:127], v[164:165], v[100:101], v[156:157] op_sel_hi:[0,1,1]
	v_pk_fma_f32 v[128:129], v[164:165], v[102:103], v[158:159] op_sel_hi:[0,1,1]
	s_waitcnt lgkmcnt(0)
; DI unsigned short f2bf(float x) { return (unsigned short)(pack2(x, 0.f) & 0xffffu); }
; DI float bflo(unsigned u) { return __uint_as_float(u << 16); }
; DI float bfhi(unsigned u) { return __uint_as_float(u & 0xffff0000u); }
; DI void scan_prep(u32x2 (&raw)[5], const float (&kkw)[4], const float (&kaw)[4], float* dst  ) {
;   vm_wait5x2(raw[0], raw[1], raw[2], raw[3], raw[4]);
;   float r[4] = {bflo(raw[0].x), bfhi(raw[0].x), bflo(raw[0].y), bfhi(raw[0].y)};
;   float k[4] = {bflo(raw[1].x), bfhi(raw[1].x), bflo(raw[1].y), bfhi(raw[1].y)};
;   float v[4] = {bflo(raw[2].x), bfhi(raw[2].x), bflo(raw[2].y), bfhi(raw[2].y)};
;   float e[4] = {bflo(raw[3].x), bfhi(raw[3].x), bflo(raw[3].y), bfhi(raw[3].y)};
;   float a[4] = {bflo(raw[4].x), bfhi(raw[4].x), bflo(raw[4].y), bfhi(raw[4].y)};
;   float kr[4], ss = 0.f;
; #pragma unroll
;   for (int i = 0; i < 4; ++i) { kr[i] = mul_(k[i], kkw[i]); ss = (i < 3) ? fma_(kr[i], kr[i], ss) : fma_n_(kr[i], kr[i], ss); }
;   ss = reduce16(ss);
;   const float inv = __builtin_amdgcn_rcpf(fmaxf(__builtin_amdgcn_sqrtf(ss), 1e-12f));
;   float w4[4], kd4[4], a4[4], b4[4];
; #pragma unroll
;   for (int i = 0; i < 4; ++i) {
;     float kn = kr[i] * inv;
;     w4[i] = __builtin_amdgcn_exp2f(mul_(e[i], -LOG2E));
;     kd4[i] = mul_(k[i], fma_(add_(a[i], -1.f), kaw[i], 1.f));
;     a4[i] = -kn;
;     b4[i] = mul_(kn, a[i]);
;   }
;   *(float4*)(dst) = float4{r[0], r[1], r[2], r[3]};
;   *(float4*)(dst + 64) = float4{w4[0], w4[1], w4[2], w4[3]};
;   *(float4*)(dst + 128) = float4{kd4[0], kd4[1], kd4[2], kd4[3]};
;   *(float4*)(dst + 192) = float4{a4[0], a4[1], a4[2], a4[3]};
;   *(float4*)(dst + 256) = float4{b4[0], b4[1], b4[2], b4[3]};
;   *(float4*)(dst + 320) = float4{v[0], v[1], v[2], v[3]};
; }
; DI void phase_scan(const Params& P, int l, char* smem) {
;     ...
;       {
;         float4 Ar[4], Aw[4], Ak[4], Aa[4], Ab[4], Br[4], Bw[4], Bk[4], Ba[4], Bb[4];
;         float Av[4], Bv[4];
;         SCAN_LOAD(A, 0);
;         SCAN_LOAD(B, 1);
;         SCAN_STEPS(A, 0);
;         SCAN_LOAD(A, 2);
;         SCAN_STEPS(B, 1);
;         SCAN_LOAD(B, 3);
;         SCAN_STEPS(A, 2);
;         SCAN_STEPS(B, 3);
;       }
;     ...
;       {
;         int i = c * 16 + kl;
;         int s = dir == 0 ? i : (i < 256 ? 255 - i : 16895 - i);
;         Y[((size_t)b * SB + s) * 1024 + st] = f2bf(ykeep);
;       }
	v_pk_mul_f32 v[164:165], v[126:127], v[136:137]
	v_pk_fma_f32 v[164:165], v[128:129], v[138:139], v[164:165]
	v_add_f32_e32 v164, v164, v165
	v_pk_fma_f32 v[160:161], v[126:127], v[140:141], v[160:161]
	v_pk_fma_f32 v[162:163], v[128:129], v[142:143], v[162:163]
	v_add_f32_dpp v164, v164, v164 quad_perm:[1,0,3,2] row_mask:0xf bank_mask:0xf bound_ctrl:1
	v_pk_mul_f32 v[166:167], v[126:127], v[104:105]
	v_pk_fma_f32 v[166:167], v[128:129], v[106:107], v[166:167]
	v_add_f32_dpp v164, v164, v164 quad_perm:[2,3,0,1] row_mask:0xf bank_mask:0xf bound_ctrl:1
	v_add_f32_e32 v26, v166, v167
	s_nop 0
	v_add_f32_dpp v164, v164, v164 row_half_mirror row_mask:0xf bank_mask:0xf bound_ctrl:1
	s_nop 0
	s_nop 0
	v_add_f32_dpp v164, v164, v164 row_mirror row_mask:0xf bank_mask:0xf bound_ctrl:1
	v_pk_fma_f32 v[126:127], v[164:165], v[144:145], v[160:161] op_sel_hi:[0,1,1]
	v_pk_fma_f32 v[128:129], v[164:165], v[146:147], v[162:163] op_sel_hi:[0,1,1]
	v_pk_mul_f32 v[166:167], v[126:127], v[148:149]
	v_pk_fma_f32 v[166:167], v[128:129], v[150:151], v[166:167]
	v_add_f32_e32 v27, v166, v167
	v_add_f32_dpp v12, v12, v12 row_ror:8 row_mask:0xf bank_mask:0x3 bound_ctrl:1
	v_add_f32_dpp v12, v20, v20 row_ror:8 row_mask:0xf bank_mask:0xc bound_ctrl:1
	v_add_f32_dpp v13, v13, v13 row_ror:8 row_mask:0xf bank_mask:0x3 bound_ctrl:1
	v_add_f32_dpp v13, v21, v21 row_ror:8 row_mask:0xf bank_mask:0xc bound_ctrl:1
	v_add_f32_dpp v14, v14, v14 row_ror:8 row_mask:0xf bank_mask:0x3 bound_ctrl:1
	v_add_f32_dpp v14, v22, v22 row_ror:8 row_mask:0xf bank_mask:0xc bound_ctrl:1
	v_add_f32_dpp v15, v15, v15 row_ror:8 row_mask:0xf bank_mask:0x3 bound_ctrl:1
	v_add_f32_dpp v15, v23, v23 row_ror:8 row_mask:0xf bank_mask:0xc bound_ctrl:1
	v_add_f32_dpp v16, v16, v16 row_ror:8 row_mask:0xf bank_mask:0x3 bound_ctrl:1
	v_add_f32_dpp v16, v24, v24 row_ror:8 row_mask:0xf bank_mask:0xc bound_ctrl:1
	v_add_f32_dpp v17, v17, v17 row_ror:8 row_mask:0xf bank_mask:0x3 bound_ctrl:1
	v_add_f32_dpp v17, v25, v25 row_ror:8 row_mask:0xf bank_mask:0xc bound_ctrl:1
	v_add_f32_dpp v18, v18, v18 row_ror:8 row_mask:0xf bank_mask:0x3 bound_ctrl:1
	v_add_f32_dpp v18, v26, v26 row_ror:8 row_mask:0xf bank_mask:0xc bound_ctrl:1
	v_add_f32_dpp v19, v19, v19 row_ror:8 row_mask:0xf bank_mask:0x3 bound_ctrl:1
	v_add_f32_dpp v19, v27, v27 row_ror:8 row_mask:0xf bank_mask:0xc bound_ctrl:1
	v_add_f32_dpp v12, v12, v12 row_half_mirror row_mask:0xf bank_mask:0x5 bound_ctrl:1
	v_add_f32_dpp v12, v16, v16 row_half_mirror row_mask:0xf bank_mask:0xa bound_ctrl:1
	v_add_f32_dpp v13, v13, v13 row_half_mirror row_mask:0xf bank_mask:0x5 bound_ctrl:1
	v_add_f32_dpp v13, v17, v17 row_half_mirror row_mask:0xf bank_mask:0xa bound_ctrl:1
	v_add_f32_dpp v14, v14, v14 row_half_mirror row_mask:0xf bank_mask:0x5 bound_ctrl:1
	v_add_f32_dpp v14, v18, v18 row_half_mirror row_mask:0xf bank_mask:0xa bound_ctrl:1
	v_add_f32_dpp v15, v15, v15 row_half_mirror row_mask:0xf bank_mask:0x5 bound_ctrl:1
	v_add_f32_dpp v15, v19, v19 row_half_mirror row_mask:0xf bank_mask:0xa bound_ctrl:1
	s_mov_b32 s10, 0x33333333
	s_mov_b32 s11, 0x33333333
	v_add_f32_dpp v28, v12, v12 quad_perm:[2,3,0,1] row_mask:0xf bank_mask:0xf bound_ctrl:1
	v_add_f32_dpp v29, v14, v14 quad_perm:[2,3,0,1] row_mask:0xf bank_mask:0xf bound_ctrl:1
	v_add_f32_dpp v30, v13, v13 quad_perm:[2,3,0,1] row_mask:0xf bank_mask:0xf bound_ctrl:1
	v_add_f32_dpp v31, v15, v15 quad_perm:[2,3,0,1] row_mask:0xf bank_mask:0xf bound_ctrl:1
	v_cndmask_b32_e64 v28, v29, v28, s[10:11]
	v_cndmask_b32_e64 v30, v31, v30, s[10:11]
	s_mov_b32 s10, 0x55555555
	s_mov_b32 s11, 0x55555555
	s_nop 0
	v_add_f32_dpp v29, v28, v28 quad_perm:[1,0,3,2] row_mask:0xf bank_mask:0xf bound_ctrl:1
	v_add_f32_dpp v31, v30, v30 quad_perm:[1,0,3,2] row_mask:0xf bank_mask:0xf bound_ctrl:1
	v_cndmask_b32_e64 v11, v31, v29, s[10:11]
	v_add_u32_e32 v10, s9, v216
	v_cndmask_b32_e64 v10, v10, v217, s[4:5]
	v_cvt_pk_bf16_f32 v12, v11, s0
	v_ashrrev_i32_e32 v11, 31, v10
	v_lshl_add_u64 v[10:11], s[6:7], 0, v[10:11]
	v_lshlrev_b64 v[10:11], 11, v[10:11]
	v_lshl_add_u64 v[10:11], v[188:189], 0, v[10:11]
	global_store_short v[10:11], v12, off
	s_cbranch_vccnz .LBB0_510
	s_waitcnt vmcnt(4)
	v_lshlrev_b32_e32 v11, 16, v176
	v_mul_f32 v12, v11, v2
	v_and_b32_e32 v15, 0xffff0000, v176
	v_fma_f32 v10, v12, v12, v1
	v_mul_f32 v13, v15, v3
	v_lshlrev_b32_e32 v16, 16, v177
	v_fma_f32 v10, v13, v13, v10
	v_mul_f32 v28, v16, v4
	v_and_b32_e32 v17, 0xffff0000, v177
	v_fma_f32 v10, v28, v28, v10
	v_mul_f32 v29, v17, v5
	s_waitcnt vmcnt(2)
	v_lshlrev_b32_e32 v14, 16, v178
	v_fma_f32 v10, v29, v29, v10
	s_nop 1
	s_waitcnt vmcnt(1)
	v_lshlrev_b32_e32 v26, 16, v182
	v_lshlrev_b32_e32 v33, 16, v179
	v_add_f32_dpp v10, v10, v10 quad_perm:[1,0,3,2] row_mask:0xf bank_mask:0xf bound_ctrl:1
	v_and_b32_e32 v27, 0xffff0000, v182
	v_and_b32_e32 v30, 0xffff0000, v178
	v_add_f32_dpp v10, v10, v10 quad_perm:[2,3,0,1] row_mask:0xf bank_mask:0xf bound_ctrl:1
	v_lshlrev_b32_e32 v35, 16, v183
	v_and_b32_e32 v37, 0xffff0000, v179
	v_add_f32_dpp v10, v10, v10 row_half_mirror row_mask:0xf bank_mask:0xf bound_ctrl:1
	s_bitcmp1_b32 s8, 0
	s_cselect_b32 s9, 0x6000, 0
	v_add_f32_dpp v10, v10, v10 row_mirror row_mask:0xf bank_mask:0xf bound_ctrl:1
	v_sqrt_f32_e32 v10, v10
	v_add_u32_e32 v34, s9, v192
	v_and_b32_e32 v36, 0xffff0000, v183
	v_and_b32_e32 v25, 0xffff0000, v175
	v_max_f32_e32 v10, 0x2b8cbccc, v10
	v_rcp_f32_e32 v32, v10
	v_mul_f32 v10, v14, v196
	v_add_f32 v14, v26, v197
	v_lshlrev_b32_e32 v24, 16, v175
	v_fma_f32 v14, v14, v6, v198
	v_pk_mul_f32 v[12:13], v[12:13], v[32:33] op_sel_hi:[1,0]
	v_mul_f32 v14, v11, v14
	v_mul_f32 v11, v30, v196
	v_add_f32 v30, v27, v197
	v_exp_f32_e32 v10, v10
	v_xor_b32_e32 v31, 0x80000000, v13
	v_mul_f32 v27, v13, v27
	v_add_f32 v13, v35, v197
	v_fma_f32 v30, v30, v7, v198
	v_mul_f32 v26, v12, v26
	v_exp_f32_e32 v11, v11
	v_fma_f32 v13, v13, v8, v198
	v_mul_f32 v15, v15, v30
	v_xor_b32_e32 v30, 0x80000000, v12
	v_mul_f32 v12, v33, v196
	v_mul_f32 v16, v16, v13
	v_mul_f32 v13, v37, v196
	v_pk_mul_f32 v[28:29], v[28:29], v[32:33] op_sel_hi:[1,0]
	v_exp_f32_e32 v12, v12
	v_exp_f32_e32 v13, v13
	v_and_b32_e32 v23, 0xffff0000, v174
	v_lshlrev_b32_e32 v22, 16, v174
	v_xor_b32_e32 v32, 0x80000000, v28
	v_mul_f32 v28, v28, v35
	v_add_f32 v35, v36, v197
	v_and_b32_e32 v21, 0xffff0000, v181
	v_lshlrev_b32_e32 v20, 16, v181
	v_and_b32_e32 v19, 0xffff0000, v180
	v_lshlrev_b32_e32 v18, 16, v180
	v_xor_b32_e32 v33, 0x80000000, v29
	v_fma_f32 v35, v35, v9, v198
	v_mul_f32 v29, v29, v36
	s_nop 0
	v_mul_f32 v17, v17, v35
	ds_write_b128 v34, v[22:25]
	ds_write_b128 v34, v[10:13] offset:256
	ds_write_b128 v34, v[14:17] offset:512
	ds_write_b128 v34, v[30:33] offset:768
	ds_write_b128 v34, v[26:29] offset:1024
	ds_write_b128 v34, v[18:21] offset:1280
	s_branch .LBB0_510
